# peeled first K-tile of every output tile: first MFMA of each accumulator chain uses srcC=0, the 128 v_mov accumulator zeroing per tile is gone
# speedup vs baseline: 1.0223x; 1.0031x over previous
; #define PG8_STAGE(bufoff, gbase, voff) do { _Pragma("unroll") for (int _i = 0; _i < 2; ++_i) \
;     __builtin_amdgcn_global_load_lds((const unsigned*)((const char*)(gbase) + (voff)[_i]), (LAS unsigned*)(lds + (bufoff) + ldsw + _i * 8192), 16, 0, 0); } while (0)
; #define PG8_LDA(dst, b, h) do { _Pragma("unroll") for (int m = 0; m < 4; ++m) _Pragma("unroll") for (int k = 0; k < 2; ++k) dst[m][k] = *(const LAS bf16x8*)(lds + PG8_SA(b, h) + aoff + m * 2048 + k * 1024); } while (0)
; #define PG8_LDB(dst, b, h) do { _Pragma("unroll") for (int n = 0; n < 2; ++n) _Pragma("unroll") for (int k = 0; k < 2; ++k) dst[n][k] = *(const LAS bf16x8*)(lds + PG8_SB(b, h) + boff + n * 2048 + k * 1024); } while (0)
; #define PG8_MMA(ai, bj, At, Bt) do { __builtin_amdgcn_s_setprio(1); _Pragma("unroll") for (int m = 0; m < 4; ++m) _Pragma("unroll") for (int n = 0; n < 2; ++n) _Pragma("unroll") for (int k = 0; k < 2; ++k) \
;     acc[ai][bj][m][n] = __builtin_amdgcn_mfma_f32_16x16x32_bf16(Bt[n][k], At[m][k], acc[ai][bj][m][n], 0, 0, 0); __builtin_amdgcn_s_setprio(0); } while (0)
; #define PG8_WAIT_V(n) asm volatile("s_waitcnt vmcnt(" #n ")" ::: "memory")
; #define PG8_WAIT_L(n) asm volatile("s_waitcnt lgkmcnt(" #n ")" ::: "memory")
; #define PG8_BAR __builtin_amdgcn_s_barrier()
; #define PG8_SCHED __builtin_amdgcn_sched_barrier(0)
; __device__ __forceinline__ void gemm_phase(const Ctx& cx, LAS unsigned char* lds, const GemmDesc& g) {
;     ...
;     for (int t = 0; t < nt; t += 2) {
;       const bool last = (t == nt - 2);
;       const char* a1 = ktile_ptr(cA1, cA2, t + 1, ksplit, kstepA);
;       const char* a2 = last ? ktile_ptr(nA1, nA2, 0, ksplit, kstepA) : ktile_ptr(cA1, cA2, t + 2, ksplit, kstepA);
;       const char* a3 = last ? ktile_ptr(nA1, nA2, 1, ksplit, kstepA) : ktile_ptr(cA1, cA2, t + 3, ksplit, kstepA);
;       const char* b2 = last ? nB : cB + (size_t)(t + 2) * kstepB; const char* b3 = b2 + kstepB;
;       PG8_LDB(B0, 0, 0); PG8_LDB(B1, 0, 1); PG8_SCHED; PG8_LDA(At, 0, 0); PG8_STAGE(PG8_SA(1, 1), a1 + hstepA, voffA);
;       PG8_WAIT_V(8); PG8_WAIT_L(0); PG8_BAR; PG8_MMA(0, 0, At, B0); PG8_MMA(0, 1, At, B1); PG8_BAR; PG8_SCHED;
.LBB0_357:
	s_add_u32 s12, s60, s18
	s_addc_u32 s13, s61, s19
	s_add_u32 s16, s24, s16
	s_addc_u32 s17, s25, s17
	s_add_u32 s20, s12, s68
	s_addc_u32 s21, s13, s69
	s_add_u32 s52, s14, 0x100
	s_addc_u32 s53, s15, 0
	s_mov_b32 s6, 0
	s_add_i32 s7, s6, 1
	s_sub_i32 s14, s7, s41
	s_min_u32 s76, s7, s14
	s_cmp_lt_u32 s7, s41
	s_cselect_b32 s7, s9, s17
	s_cselect_b32 s54, s8, s16
	s_lshl_b64 s[14:15], s[76:77], s80
	s_add_u32 s55, s54, s14
	s_addc_u32 s73, s7, s15
	s_add_i32 s76, 0, 0x10000
	v_add_u32_e32 v96, s76, v252
	s_add_i32 vcc_lo, 0, 0x14000
	ds_read_b128 v[130:133], v96
	ds_read_b128 v[134:137], v96 offset:1024
	ds_read_b128 v[138:141], v96 offset:2048
	ds_read_b128 v[142:145], v96 offset:3072
	v_add_u32_e32 v96, vcc_lo, v252
	ds_read_b128 v[146:149], v96
	ds_read_b128 v[150:153], v96 offset:1024
	ds_read_b128 v[154:157], v96 offset:2048
	ds_read_b128 v[158:161], v96 offset:3072
	s_add_u32 s72, s55, s28
	s_addc_u32 s73, s73, s29
	v_lshl_add_u64 v[194:195], s[72:73], 0, v[210:211]
	s_add_i32 m0, s51, 0xc000
	ds_read_b128 v[162:165], v237
	ds_read_b128 v[166:169], v237 offset:1024
	ds_read_b128 v[170:173], v237 offset:2048
	ds_read_b128 v[174:177], v237 offset:3072
	ds_read_b128 v[178:181], v237 offset:4096
	ds_read_b128 v[182:185], v237 offset:5120
	ds_read_b128 v[186:189], v237 offset:6144
	ds_read_b128 v[190:193], v237 offset:7168
	global_load_lds_dwordx4 v[194:195], off
	v_lshl_add_u64 v[194:195], s[72:73], 0, v[212:213]
	s_add_i32 m0, s51, 0xe000
	s_nop 0
	global_load_lds_dwordx4 v[194:195], off
	s_waitcnt vmcnt(8)
	s_waitcnt lgkmcnt(0)
	s_barrier
	s_setprio 1
	s_waitcnt lgkmcnt(0)
	v_mfma_f32_16x16x32_bf16 v[126:129], v[130:133], v[162:165], 0
	v_mfma_f32_16x16x32_bf16 v[126:129], v[134:137], v[166:169], v[126:129]
	s_add_i32 s54, s6, 2
	s_cmp_lt_u32 s54, s41
	v_mfma_f32_16x16x32_bf16 v[122:125], v[142:145], v[166:169], 0
	s_cselect_b64 s[14:15], -1, 0
	s_and_b64 s[58:59], s[14:15], exec
	v_mfma_f32_16x16x32_bf16 v[122:125], v[138:141], v[162:165], v[122:125]
	s_cselect_b32 s7, 0, s41
	s_sub_i32 s7, s6, s7
	v_mfma_f32_16x16x32_bf16 v[118:121], v[146:149], v[162:165], 0
	s_add_i32 s76, s7, 2
	s_and_b64 s[14:15], s[14:15], exec
	v_mfma_f32_16x16x32_bf16 v[118:121], v[150:153], v[166:169], v[118:121]
	s_cselect_b32 s7, s9, s17
	s_cselect_b32 s58, s8, s16
	v_mfma_f32_16x16x32_bf16 v[114:117], v[158:161], v[166:169], 0
	s_lshl_b64 s[14:15], s[76:77], s80
	s_add_u32 s72, s58, s14
	v_mfma_f32_16x16x32_bf16 v[114:117], v[154:157], v[162:165], v[114:117]
	s_addc_u32 s7, s7, s15
	s_add_i32 s14, s6, 3
	v_mfma_f32_16x16x32_bf16 v[98:101], v[154:157], v[170:173], 0
	s_cmp_lt_u32 s14, s41
	s_cselect_b64 s[14:15], -1, 0
	v_mfma_f32_16x16x32_bf16 v[98:101], v[158:161], v[174:177], v[98:101]
	s_and_b64 s[58:59], s[14:15], exec
	s_cselect_b32 s58, 0, s41
	v_mfma_f32_16x16x32_bf16 v[102:105], v[150:153], v[174:177], 0
	s_sub_i32 s58, s6, s58
	s_add_i32 s76, s58, 3
	v_mfma_f32_16x16x32_bf16 v[102:105], v[146:149], v[170:173], v[102:105]
	s_and_b64 s[14:15], s[14:15], exec
	s_cselect_b32 s58, s9, s17
	v_mfma_f32_16x16x32_bf16 v[106:109], v[138:141], v[170:173], 0
	s_cselect_b32 s59, s8, s16
	s_lshl_b64 s[14:15], s[76:77], s80
	v_mfma_f32_16x16x32_bf16 v[106:109], v[142:145], v[174:177], v[106:109]
	s_add_u32 s59, s59, s14
	s_addc_u32 s58, s58, s15
	v_mfma_f32_16x16x32_bf16 v[110:113], v[134:137], v[174:177], 0
	s_cmp_eq_u32 s39, s6
	s_cselect_b32 s15, s13, s7
	v_mfma_f32_16x16x32_bf16 v[110:113], v[130:133], v[170:173], v[110:113]
	s_cselect_b32 s14, s12, s72
	s_cselect_b32 s7, s21, s58
	v_mfma_f32_16x16x32_bf16 v[92:95], v[130:133], v[178:181], 0
	s_cselect_b32 s6, s20, s59
	s_cselect_b32 s59, s97, s53
	v_mfma_f32_16x16x32_bf16 v[92:95], v[134:137], v[182:185], v[92:95]
	s_cselect_b32 s58, s96, s52
	s_mov_b32 s76, 0x10000
	v_mfma_f32_16x16x32_bf16 v[88:91], v[142:145], v[182:185], 0
	v_mfma_f32_16x16x32_bf16 v[88:91], v[138:141], v[178:181], v[88:91]
	v_mfma_f32_16x16x32_bf16 v[84:87], v[146:149], v[178:181], 0
	v_mfma_f32_16x16x32_bf16 v[84:87], v[150:153], v[182:185], v[84:87]
	v_mfma_f32_16x16x32_bf16 v[80:83], v[158:161], v[182:185], 0
	v_mfma_f32_16x16x32_bf16 v[80:83], v[154:157], v[178:181], v[80:83]
	v_mfma_f32_16x16x32_bf16 v[64:67], v[154:157], v[186:189], 0
	v_mfma_f32_16x16x32_bf16 v[64:67], v[158:161], v[190:193], v[64:67]
	v_mfma_f32_16x16x32_bf16 v[68:71], v[150:153], v[190:193], 0
	v_mfma_f32_16x16x32_bf16 v[68:71], v[146:149], v[186:189], v[68:71]
	v_mfma_f32_16x16x32_bf16 v[72:75], v[138:141], v[186:189], 0
	v_mfma_f32_16x16x32_bf16 v[72:75], v[142:145], v[190:193], v[72:75]
	v_mfma_f32_16x16x32_bf16 v[76:79], v[134:137], v[190:193], 0
	v_mfma_f32_16x16x32_bf16 v[76:79], v[130:133], v[186:189], v[76:79]
	s_setprio 0
	s_barrier
; #define PG8_STAGE(bufoff, gbase, voff) do { _Pragma("unroll") for (int _i = 0; _i < 2; ++_i) \
;     __builtin_amdgcn_global_load_lds((const unsigned*)((const char*)(gbase) + (voff)[_i]), (LAS unsigned*)(lds + (bufoff) + ldsw + _i * 8192), 16, 0, 0); } while (0)
; #define PG8_LDA(dst, b, h) do { _Pragma("unroll") for (int m = 0; m < 4; ++m) _Pragma("unroll") for (int k = 0; k < 2; ++k) dst[m][k] = *(const LAS bf16x8*)(lds + PG8_SA(b, h) + aoff + m * 2048 + k * 1024); } while (0)
; #define PG8_MMA(ai, bj, At, Bt) do { __builtin_amdgcn_s_setprio(1); _Pragma("unroll") for (int m = 0; m < 4; ++m) _Pragma("unroll") for (int n = 0; n < 2; ++n) _Pragma("unroll") for (int k = 0; k < 2; ++k) \
;     acc[ai][bj][m][n] = __builtin_amdgcn_mfma_f32_16x16x32_bf16(Bt[n][k], At[m][k], acc[ai][bj][m][n], 0, 0, 0); __builtin_amdgcn_s_setprio(0); } while (0)
; #define PG8_WAIT_V(n) asm volatile("s_waitcnt vmcnt(" #n ")" ::: "memory")
; #define PG8_WAIT_L(n) asm volatile("s_waitcnt lgkmcnt(" #n ")" ::: "memory")
; #define PG8_BAR __builtin_amdgcn_s_barrier()
; #define PG8_SCHED __builtin_amdgcn_sched_barrier(0)
; __device__ __forceinline__ void gemm_phase(const Ctx& cx, LAS unsigned char* lds, const GemmDesc& g) {
;     ...
;       PG8_LDA(At, 0, 1); PG8_STAGE(PG8_SB(0, 0), b2, voffB); PG8_STAGE(PG8_SB(0, 1), b2 + hstepB, voffB); PG8_STAGE(PG8_SA(0, 0), a2, voffA);
;       PG8_WAIT_V(8); PG8_WAIT_L(0); PG8_BAR; PG8_MMA(1, 0, At, B0); PG8_MMA(1, 1, At, B1); PG8_BAR; PG8_SCHED;
	s_add_i32 s55, s76, s36
	v_lshl_add_u64 v[194:195], s[58:59], 0, v[216:217]
	s_mov_b32 m0, s55
	ds_read_b128 v[162:165], v237 offset:16384
	ds_read_b128 v[166:169], v237 offset:17408
	ds_read_b128 v[170:173], v237 offset:18432
	ds_read_b128 v[174:177], v237 offset:19456
	ds_read_b128 v[178:181], v237 offset:20480
	ds_read_b128 v[182:185], v237 offset:21504
	ds_read_b128 v[186:189], v237 offset:22528
	ds_read_b128 v[190:193], v237 offset:23552
	global_load_lds_dwordx4 v[194:195], off
	s_add_i32 m0, s55, 0x2000
	v_lshl_add_u64 v[196:197], s[58:59], 0, v[214:215]
	s_add_u32 s58, s58, s30
	s_addc_u32 s59, s59, s31
	s_add_i32 s55, vcc_lo, s36
	global_load_lds_dwordx4 v[196:197], off
	v_lshl_add_u64 v[198:199], s[58:59], 0, v[216:217]
	s_mov_b32 m0, s55
	v_lshl_add_u64 v[200:201], s[58:59], 0, v[214:215]
	global_load_lds_dwordx4 v[198:199], off
	s_add_i32 m0, s55, 0x2000
	v_lshl_add_u64 v[202:203], s[14:15], 0, v[210:211]
	global_load_lds_dwordx4 v[200:201], off
	s_mov_b32 m0, s51
	s_nop 0
	global_load_lds_dwordx4 v[202:203], off
	v_lshl_add_u64 v[202:203], s[14:15], 0, v[212:213]
	s_mov_b32 m0, s43
	s_nop 0
	global_load_lds_dwordx4 v[202:203], off
	s_waitcnt vmcnt(8)
	s_waitcnt lgkmcnt(0)
	s_barrier
	s_setprio 1
	s_waitcnt lgkmcnt(0)
	v_mfma_f32_16x16x32_bf16 v[60:63], v[130:133], v[162:165], 0
	v_mfma_f32_16x16x32_bf16 v[60:63], v[134:137], v[166:169], v[60:63]
	v_mfma_f32_16x16x32_bf16 v[56:59], v[142:145], v[166:169], 0
	v_mfma_f32_16x16x32_bf16 v[56:59], v[138:141], v[162:165], v[56:59]
	v_mfma_f32_16x16x32_bf16 v[52:55], v[146:149], v[162:165], 0
	v_mfma_f32_16x16x32_bf16 v[52:55], v[150:153], v[166:169], v[52:55]
	v_mfma_f32_16x16x32_bf16 v[48:51], v[158:161], v[166:169], 0
	v_mfma_f32_16x16x32_bf16 v[48:51], v[154:157], v[162:165], v[48:51]
	v_mfma_f32_16x16x32_bf16 v[32:35], v[154:157], v[170:173], 0
	v_mfma_f32_16x16x32_bf16 v[32:35], v[158:161], v[174:177], v[32:35]
	v_mfma_f32_16x16x32_bf16 v[36:39], v[150:153], v[174:177], 0
	v_mfma_f32_16x16x32_bf16 v[36:39], v[146:149], v[170:173], v[36:39]
	v_mfma_f32_16x16x32_bf16 v[40:43], v[138:141], v[170:173], 0
	v_mfma_f32_16x16x32_bf16 v[40:43], v[142:145], v[174:177], v[40:43]
	v_mfma_f32_16x16x32_bf16 v[44:47], v[134:137], v[174:177], 0
	v_mfma_f32_16x16x32_bf16 v[44:47], v[130:133], v[170:173], v[44:47]
	v_mfma_f32_16x16x32_bf16 v[28:31], v[130:133], v[178:181], 0
	v_mfma_f32_16x16x32_bf16 v[28:31], v[134:137], v[182:185], v[28:31]
	v_mfma_f32_16x16x32_bf16 v[24:27], v[142:145], v[182:185], 0
	v_mfma_f32_16x16x32_bf16 v[24:27], v[138:141], v[178:181], v[24:27]
	v_mfma_f32_16x16x32_bf16 v[20:23], v[146:149], v[178:181], 0
	v_mfma_f32_16x16x32_bf16 v[20:23], v[150:153], v[182:185], v[20:23]
	v_mfma_f32_16x16x32_bf16 v[16:19], v[158:161], v[182:185], 0
	v_mfma_f32_16x16x32_bf16 v[16:19], v[154:157], v[178:181], v[16:19]
	v_mfma_f32_16x16x32_bf16 v[0:3], v[154:157], v[186:189], 0
	v_mfma_f32_16x16x32_bf16 v[0:3], v[158:161], v[190:193], v[0:3]
	v_mfma_f32_16x16x32_bf16 v[4:7], v[150:153], v[190:193], 0
	v_mfma_f32_16x16x32_bf16 v[4:7], v[146:149], v[186:189], v[4:7]
	v_mfma_f32_16x16x32_bf16 v[8:11], v[138:141], v[186:189], 0
	v_mfma_f32_16x16x32_bf16 v[8:11], v[142:145], v[190:193], v[8:11]
	v_mfma_f32_16x16x32_bf16 v[12:15], v[134:137], v[190:193], 0
	v_mfma_f32_16x16x32_bf16 v[12:15], v[130:133], v[186:189], v[12:15]
	s_setprio 0
	s_barrier
	s_branch .Lk_p2

; #define PG8_STAGE(bufoff, gbase, voff) do { _Pragma("unroll") for (int _i = 0; _i < 2; ++_i) \
;     __builtin_amdgcn_global_load_lds((const unsigned*)((const char*)(gbase) + (voff)[_i]), (LAS unsigned*)(lds + (bufoff) + ldsw + _i * 8192), 16, 0, 0); } while (0)
; #define PG8_LDA(dst, b, h) do { _Pragma("unroll") for (int m = 0; m < 4; ++m) _Pragma("unroll") for (int k = 0; k < 2; ++k) dst[m][k] = *(const LAS bf16x8*)(lds + PG8_SA(b, h) + aoff + m * 2048 + k * 1024); } while (0)
; #define PG8_LDB(dst, b, h) do { _Pragma("unroll") for (int n = 0; n < 2; ++n) _Pragma("unroll") for (int k = 0; k < 2; ++k) dst[n][k] = *(const LAS bf16x8*)(lds + PG8_SB(b, h) + boff + n * 2048 + k * 1024); } while (0)
; #define PG8_MMA(ai, bj, At, Bt) do { __builtin_amdgcn_s_setprio(1); _Pragma("unroll") for (int m = 0; m < 4; ++m) _Pragma("unroll") for (int n = 0; n < 2; ++n) _Pragma("unroll") for (int k = 0; k < 2; ++k) \
;     acc[ai][bj][m][n] = __builtin_amdgcn_mfma_f32_16x16x32_bf16(Bt[n][k], At[m][k], acc[ai][bj][m][n], 0, 0, 0); __builtin_amdgcn_s_setprio(0); } while (0)
; #define PG8_WAIT_V(n) asm volatile("s_waitcnt vmcnt(" #n ")" ::: "memory")
; #define PG8_WAIT_L(n) asm volatile("s_waitcnt lgkmcnt(" #n ")" ::: "memory")
; #define PG8_BAR __builtin_amdgcn_s_barrier()
; #define PG8_SCHED __builtin_amdgcn_sched_barrier(0)
; __device__ __forceinline__ void gemm_phase(const Ctx& cx, LAS unsigned char* lds, const GemmDesc& g) {
;     ...
;       PG8_LDB(B0, 1, 0); PG8_LDB(B1, 1, 1); PG8_SCHED; PG8_LDA(At, 1, 0); PG8_STAGE(PG8_SA(0, 1), a2 + hstepA, voffA);
;       PG8_WAIT_V(8); PG8_WAIT_L(0); PG8_BAR; PG8_MMA(0, 0, At, B0); PG8_MMA(0, 1, At, B1); PG8_BAR; PG8_SCHED;
.Lk_p2:
	s_add_i32 s55, 0, 0x18000
	v_add_u32_e32 v96, s55, v252
	s_add_i32 s58, 0, 0x1c000
	ds_read_b128 v[130:133], v96
	ds_read_b128 v[134:137], v96 offset:1024
	ds_read_b128 v[138:141], v96 offset:2048
	ds_read_b128 v[142:145], v96 offset:3072
	v_add_u32_e32 v96, s58, v252
	ds_read_b128 v[146:149], v96
	ds_read_b128 v[150:153], v96 offset:1024
	ds_read_b128 v[154:157], v96 offset:2048
	ds_read_b128 v[158:161], v96 offset:3072
	s_add_u32 s14, s14, s28
	s_addc_u32 s15, s15, s29
	s_mov_b32 m0, s40
	v_lshl_add_u64 v[202:203], s[14:15], 0, v[210:211]
	ds_read_b128 v[162:165], v237 offset:32768
	ds_read_b128 v[166:169], v237 offset:33792
	ds_read_b128 v[170:173], v237 offset:34816
	ds_read_b128 v[174:177], v237 offset:35840
	ds_read_b128 v[178:181], v237 offset:36864
	ds_read_b128 v[182:185], v237 offset:37888
	ds_read_b128 v[186:189], v237 offset:38912
	ds_read_b128 v[190:193], v237 offset:39936
	global_load_lds_dwordx4 v[202:203], off
	v_lshl_add_u64 v[202:203], s[14:15], 0, v[212:213]
	s_mov_b32 m0, s37
	s_nop 0
	global_load_lds_dwordx4 v[202:203], off
	s_waitcnt vmcnt(8)
	s_waitcnt lgkmcnt(0)
	s_barrier
	s_setprio 1
	s_waitcnt lgkmcnt(0)
	v_mfma_f32_16x16x32_bf16 v[126:129], v[130:133], v[162:165], v[126:129]
	v_mfma_f32_16x16x32_bf16 v[126:129], v[134:137], v[166:169], v[126:129]
	v_mfma_f32_16x16x32_bf16 v[122:125], v[142:145], v[166:169], v[122:125]
	v_mfma_f32_16x16x32_bf16 v[122:125], v[138:141], v[162:165], v[122:125]
	v_mfma_f32_16x16x32_bf16 v[118:121], v[146:149], v[162:165], v[118:121]
	v_mfma_f32_16x16x32_bf16 v[118:121], v[150:153], v[166:169], v[118:121]
	v_mfma_f32_16x16x32_bf16 v[114:117], v[158:161], v[166:169], v[114:117]
	v_mfma_f32_16x16x32_bf16 v[114:117], v[154:157], v[162:165], v[114:117]
	v_mfma_f32_16x16x32_bf16 v[98:101], v[154:157], v[170:173], v[98:101]
	v_mfma_f32_16x16x32_bf16 v[98:101], v[158:161], v[174:177], v[98:101]
	v_mfma_f32_16x16x32_bf16 v[102:105], v[150:153], v[174:177], v[102:105]
	v_mfma_f32_16x16x32_bf16 v[102:105], v[146:149], v[170:173], v[102:105]
	v_mfma_f32_16x16x32_bf16 v[106:109], v[138:141], v[170:173], v[106:109]
	v_mfma_f32_16x16x32_bf16 v[106:109], v[142:145], v[174:177], v[106:109]
	v_mfma_f32_16x16x32_bf16 v[110:113], v[134:137], v[174:177], v[110:113]
	v_mfma_f32_16x16x32_bf16 v[110:113], v[130:133], v[170:173], v[110:113]
	v_mfma_f32_16x16x32_bf16 v[92:95], v[130:133], v[178:181], v[92:95]
	v_mfma_f32_16x16x32_bf16 v[92:95], v[134:137], v[182:185], v[92:95]
	v_mfma_f32_16x16x32_bf16 v[88:91], v[142:145], v[182:185], v[88:91]
	v_mfma_f32_16x16x32_bf16 v[88:91], v[138:141], v[178:181], v[88:91]
	v_mfma_f32_16x16x32_bf16 v[84:87], v[146:149], v[178:181], v[84:87]
	v_mfma_f32_16x16x32_bf16 v[84:87], v[150:153], v[182:185], v[84:87]
	v_mfma_f32_16x16x32_bf16 v[80:83], v[158:161], v[182:185], v[80:83]
	v_mfma_f32_16x16x32_bf16 v[80:83], v[154:157], v[178:181], v[80:83]
	v_mfma_f32_16x16x32_bf16 v[64:67], v[154:157], v[186:189], v[64:67]
	v_mfma_f32_16x16x32_bf16 v[64:67], v[158:161], v[190:193], v[64:67]
	v_mfma_f32_16x16x32_bf16 v[68:71], v[150:153], v[190:193], v[68:71]
	v_mfma_f32_16x16x32_bf16 v[68:71], v[146:149], v[186:189], v[68:71]
	v_mfma_f32_16x16x32_bf16 v[72:75], v[138:141], v[186:189], v[72:75]
	v_mfma_f32_16x16x32_bf16 v[72:75], v[142:145], v[190:193], v[72:75]
	v_mfma_f32_16x16x32_bf16 v[76:79], v[134:137], v[190:193], v[76:79]
	v_mfma_f32_16x16x32_bf16 v[76:79], v[130:133], v[186:189], v[76:79]
	s_setprio 0
	s_barrier
; #define PG8_STAGE(bufoff, gbase, voff) do { _Pragma("unroll") for (int _i = 0; _i < 2; ++_i) \
;     __builtin_amdgcn_global_load_lds((const unsigned*)((const char*)(gbase) + (voff)[_i]), (LAS unsigned*)(lds + (bufoff) + ldsw + _i * 8192), 16, 0, 0); } while (0)
; #define PG8_LDA(dst, b, h) do { _Pragma("unroll") for (int m = 0; m < 4; ++m) _Pragma("unroll") for (int k = 0; k < 2; ++k) dst[m][k] = *(const LAS bf16x8*)(lds + PG8_SA(b, h) + aoff + m * 2048 + k * 1024); } while (0)
; #define PG8_MMA(ai, bj, At, Bt) do { __builtin_amdgcn_s_setprio(1); _Pragma("unroll") for (int m = 0; m < 4; ++m) _Pragma("unroll") for (int n = 0; n < 2; ++n) _Pragma("unroll") for (int k = 0; k < 2; ++k) \
;     acc[ai][bj][m][n] = __builtin_amdgcn_mfma_f32_16x16x32_bf16(Bt[n][k], At[m][k], acc[ai][bj][m][n], 0, 0, 0); __builtin_amdgcn_s_setprio(0); } while (0)
; #define PG8_WAIT_V(n) asm volatile("s_waitcnt vmcnt(" #n ")" ::: "memory")
; #define PG8_WAIT_L(n) asm volatile("s_waitcnt lgkmcnt(" #n ")" ::: "memory")
; #define PG8_BAR __builtin_amdgcn_s_barrier()
; #define PG8_SCHED __builtin_amdgcn_sched_barrier(0)
; __device__ __forceinline__ void gemm_phase(const Ctx& cx, LAS unsigned char* lds, const GemmDesc& g) {
;     ...
;       PG8_LDA(At, 1, 1); PG8_STAGE(PG8_SB(1, 0), b3, voffB); PG8_STAGE(PG8_SB(1, 1), b3 + hstepB, voffB); PG8_STAGE(PG8_SA(1, 0), a3, voffA);
;       PG8_WAIT_V(8); PG8_WAIT_L(0); PG8_BAR; PG8_MMA(1, 0, At, B0); PG8_MMA(1, 1, At, B1); PG8_BAR; PG8_SCHED;
;     }
;     if (wr == 0) PG8_BAR;
	s_add_i32 s14, s55, s36
	v_lshl_add_u64 v[194:195], v[194:195], 0, s[92:93]
	s_mov_b32 m0, s14
	ds_read_b128 v[162:165], v237 offset:49152
	ds_read_b128 v[166:169], v237 offset:50176
	ds_read_b128 v[170:173], v237 offset:51200
	ds_read_b128 v[174:177], v237 offset:52224
	ds_read_b128 v[178:181], v237 offset:53248
	ds_read_b128 v[182:185], v237 offset:54272
	ds_read_b128 v[186:189], v237 offset:55296
	ds_read_b128 v[190:193], v237 offset:56320
	global_load_lds_dwordx4 v[194:195], off
	v_lshl_add_u64 v[194:195], v[196:197], 0, s[92:93]
	s_add_i32 m0, s14, 0x2000
	s_add_i32 s14, s58, s36
	global_load_lds_dwordx4 v[194:195], off
	v_lshl_add_u64 v[194:195], v[198:199], 0, s[92:93]
	s_mov_b32 m0, s14
	s_nop 0
	global_load_lds_dwordx4 v[194:195], off
	v_lshl_add_u64 v[194:195], v[200:201], 0, s[92:93]
	s_add_i32 m0, s14, 0x2000
	s_nop 0
	global_load_lds_dwordx4 v[194:195], off
	v_lshl_add_u64 v[194:195], s[6:7], 0, v[210:211]
	s_mov_b32 m0, s0
	s_nop 0
	global_load_lds_dwordx4 v[194:195], off
	v_lshl_add_u64 v[194:195], s[6:7], 0, v[212:213]
	s_mov_b32 m0, s1
	s_nop 0
	global_load_lds_dwordx4 v[194:195], off
	s_waitcnt vmcnt(8)
	s_waitcnt lgkmcnt(0)
	s_barrier
	s_setprio 1
	s_waitcnt lgkmcnt(0)
	v_mfma_f32_16x16x32_bf16 v[60:63], v[130:133], v[162:165], v[60:63]
	v_mfma_f32_16x16x32_bf16 v[60:63], v[134:137], v[166:169], v[60:63]
	v_mfma_f32_16x16x32_bf16 v[56:59], v[142:145], v[166:169], v[56:59]
	v_mfma_f32_16x16x32_bf16 v[56:59], v[138:141], v[162:165], v[56:59]
	v_mfma_f32_16x16x32_bf16 v[52:55], v[146:149], v[162:165], v[52:55]
	v_mfma_f32_16x16x32_bf16 v[52:55], v[150:153], v[166:169], v[52:55]
	v_mfma_f32_16x16x32_bf16 v[48:51], v[158:161], v[166:169], v[48:51]
	v_mfma_f32_16x16x32_bf16 v[48:51], v[154:157], v[162:165], v[48:51]
	v_mfma_f32_16x16x32_bf16 v[32:35], v[154:157], v[170:173], v[32:35]
	v_mfma_f32_16x16x32_bf16 v[32:35], v[158:161], v[174:177], v[32:35]
	v_mfma_f32_16x16x32_bf16 v[36:39], v[150:153], v[174:177], v[36:39]
	v_mfma_f32_16x16x32_bf16 v[36:39], v[146:149], v[170:173], v[36:39]
	v_mfma_f32_16x16x32_bf16 v[40:43], v[138:141], v[170:173], v[40:43]
	v_mfma_f32_16x16x32_bf16 v[40:43], v[142:145], v[174:177], v[40:43]
	v_mfma_f32_16x16x32_bf16 v[44:47], v[134:137], v[174:177], v[44:47]
	v_mfma_f32_16x16x32_bf16 v[44:47], v[130:133], v[170:173], v[44:47]
	v_mfma_f32_16x16x32_bf16 v[28:31], v[130:133], v[178:181], v[28:31]
	v_mfma_f32_16x16x32_bf16 v[28:31], v[134:137], v[182:185], v[28:31]
	v_mfma_f32_16x16x32_bf16 v[24:27], v[142:145], v[182:185], v[24:27]
	v_mfma_f32_16x16x32_bf16 v[24:27], v[138:141], v[178:181], v[24:27]
	v_mfma_f32_16x16x32_bf16 v[20:23], v[146:149], v[178:181], v[20:23]
	v_mfma_f32_16x16x32_bf16 v[20:23], v[150:153], v[182:185], v[20:23]
	v_mfma_f32_16x16x32_bf16 v[16:19], v[158:161], v[182:185], v[16:19]
	v_mfma_f32_16x16x32_bf16 v[16:19], v[154:157], v[178:181], v[16:19]
	v_mfma_f32_16x16x32_bf16 v[0:3], v[154:157], v[186:189], v[0:3]
	v_mfma_f32_16x16x32_bf16 v[0:3], v[158:161], v[190:193], v[0:3]
	v_mfma_f32_16x16x32_bf16 v[4:7], v[150:153], v[190:193], v[4:7]
	v_mfma_f32_16x16x32_bf16 v[4:7], v[146:149], v[186:189], v[4:7]
	v_mfma_f32_16x16x32_bf16 v[8:11], v[138:141], v[186:189], v[8:11]
	v_mfma_f32_16x16x32_bf16 v[8:11], v[142:145], v[190:193], v[8:11]
	v_mfma_f32_16x16x32_bf16 v[12:15], v[134:137], v[190:193], v[12:15]
	v_mfma_f32_16x16x32_bf16 v[12:15], v[130:133], v[186:189], v[12:15]
	s_setprio 0
	s_barrier
	s_add_u32 s52, s52, 0x100
	s_addc_u32 s53, s53, 0
	s_cmp_ge_u32 s54, s10
	s_mov_b32 s6, s54
	s_cbranch_scc0 .LBB0_358
	v_readlane_b32 s6, v255, 19
	v_readlane_b32 s7, v255, 20
	s_and_b64 vcc, exec, s[6:7]
	s_cbranch_vccz .LBB0_361
	s_barrier
